# diff-attention lambda computed once per wave per phase and kept in an SGPR; CMP second GEMM operand loads batched under counted waits
# baseline (speedup 1.0000x reference)
; DI float ex2(float x) { return __builtin_amdgcn_exp2f(x); }
; DI void attn_unit(const Params& p, int l, int b, int qtp, int grp, char* smem) {
;     ...
;   if (grp == 0) {
;     const float lam_init = 0.8f - 0.6f * __expf(-0.3f * (float)l);
;     float d1 = 0.f, d2 = 0.f;
;     for (int i = 0; i < 32; ++i) { d1 += p.lq1[l * 32 + i] * p.lk1[l * 32 + i]; d2 += p.lq2[l * 32 + i] * p.lk2[l * 32 + i]; }
;     const float lam = __expf(d1) - __expf(d2) + lam_init;
;     const float slope2 = ex2(-(2.f / 3.f) * (float)(3 * w + 2)) * LOG2E;
;     const float scale2 = 0.17677669529663687f * LOG2E;
.LBB0_108:
	s_mov_b32 s101, 0
	v_readlane_b32 s0, v245, 53
	v_readlane_b32 s1, v245, 54
	s_mov_b32 s4, s0
	s_lshl_b32 s0, s0, 3
	s_ashr_i32 s1, s0, 31
	s_lshl_b64 s[0:1], s[0:1], 2
	v_readlane_b32 s2, v246, 2
	v_readlane_b32 s3, v246, 3
	s_add_u32 s0, s2, s0
	s_addc_u32 s1, s3, s1
	v_writelane_b32 v245, s0, 58
	v_cvt_f32_i32_e32 v0, s4
	s_lshl_b32 s2, s4, 2
	v_writelane_b32 v245, s1, 59
	s_lshl_b32 s0, s4, 5
	s_ashr_i32 s1, s0, 31
	v_readlane_b32 s4, v247, 45
	s_lshl_b64 s[0:1], s[0:1], 2
	v_readlane_b32 s8, v247, 49
	v_writelane_b32 v245, s2, 60
	v_readlane_b32 s9, v247, 50
	s_add_u32 s2, s8, s0
	s_addc_u32 s3, s9, s1
	v_readlane_b32 s10, v247, 51
	v_writelane_b32 v245, s2, 61
	v_mul_f32_e32 v0, 0xbe99999a, v0
	v_readlane_b32 s11, v247, 52
	v_writelane_b32 v245, s3, 62
	s_add_u32 s2, s10, s0
	v_mul_f32_e32 v0, 0x3fb8aa3b, v0
	s_addc_u32 s3, s11, s1
	v_exp_f32_e32 v0, v0
	v_readlane_b32 s12, v247, 53
	v_writelane_b32 v245, s2, 63
	v_readlane_b32 s13, v247, 54
	v_readlane_b32 s14, v247, 55
	v_writelane_b32 v244, s3, 0
	s_add_u32 s2, s12, s0
	s_addc_u32 s3, s13, s1
	v_readlane_b32 s15, v247, 56
	v_writelane_b32 v244, s2, 1
	s_add_u32 s0, s14, s0
	v_fmamk_f32 v213, v0, 0xbf19999a, v155
	v_writelane_b32 v244, s3, 2
	s_addc_u32 s1, s15, s1
	v_sub_f32_e32 v214, 1.0, v213
	v_writelane_b32 v244, s0, 3
	v_mov_b32_e32 v215, 0
	v_readlane_b32 s5, v247, 46
	v_readlane_b32 s6, v247, 47
	v_readlane_b32 s7, v247, 48
	v_readlane_b32 s16, v247, 57
	v_readlane_b32 s17, v247, 58
	v_readlane_b32 s18, v247, 59
	v_readlane_b32 s19, v247, 60
	v_writelane_b32 v244, s1, 4
	s_branch .LBB0_111

; DI float ex2(float x) { return __builtin_amdgcn_exp2f(x); }
; DI void attn_unit(const Params& p, int l, int b, int qtp, int grp, char* smem) {
;     ...
;     const float lam_init = 0.8f - 0.6f * __expf(-0.3f * (float)l);
;     float d1 = 0.f, d2 = 0.f;
;     for (int i = 0; i < 32; ++i) { d1 += p.lq1[l * 32 + i] * p.lk1[l * 32 + i]; d2 += p.lq2[l * 32 + i] * p.lk2[l * 32 + i]; }
;     const float lam = __expf(d1) - __expf(d2) + lam_init;
;     const float slope2 = ex2(-(2.f / 3.f) * (float)(3 * w + 2)) * LOG2E;
;     const float scale2 = 0.17677669529663687f * LOG2E;
.LBB0_436:
	s_movk_i32 s0, 0x300
	s_and_b64 vcc, exec, s[2:3]
	s_cbranch_vccz .LBB0_110
	s_cmp_eq_u32 s101, 1
	s_cbranch_scc1 .Llam_cached
	v_readlane_b32 s0, v245, 61
	v_readlane_b32 s2, v245, 63
	v_readlane_b32 s4, v244, 1
	v_readlane_b32 s6, v244, 3
	v_readlane_b32 s1, v245, 62
	v_readlane_b32 s3, v244, 0
	v_readlane_b32 s5, v244, 2
	v_readlane_b32 s7, v244, 4
	s_nop 1
	global_load_dwordx4 v[2:5], v1, s[0:1] offset:48
	global_load_dwordx4 v[6:9], v1, s[0:1] offset:32
	global_load_dwordx4 v[10:13], v1, s[0:1] offset:16
	global_load_dwordx4 v[14:17], v1, s[0:1]
	global_load_dwordx4 v[18:21], v1, s[2:3] offset:48
	global_load_dwordx4 v[22:25], v1, s[2:3] offset:32
	global_load_dwordx4 v[26:29], v1, s[2:3] offset:16
	global_load_dwordx4 v[30:33], v1, s[2:3]
	global_load_dwordx4 v[34:37], v1, s[4:5] offset:48
	global_load_dwordx4 v[38:41], v1, s[4:5] offset:32
	global_load_dwordx4 v[42:45], v1, s[4:5] offset:16
	global_load_dwordx4 v[46:49], v1, s[4:5]
	global_load_dwordx4 v[50:53], v1, s[6:7] offset:48
	global_load_dwordx4 v[54:57], v1, s[6:7] offset:32
	global_load_dwordx4 v[58:61], v1, s[6:7] offset:16
	global_load_dwordx4 v[62:65], v1, s[6:7]
	s_mov_b32 s10, 0x2aaaaaab
	v_readlane_b32 s16, v244, 13
	v_readlane_b32 s17, v244, 14
	v_readlane_b32 s17, v244, 11
	s_movk_i32 s15, 0x1e00
	s_movk_i32 s11, 0x7f
	v_lshlrev_b32_e32 v159, 6, v151
	v_readlane_b32 s22, v244, 19
	v_lshlrev_b32_e32 v220, 2, v192
	v_lshl_or_b32 v225, v191, 5, 31
	v_sub_u32_e32 v226, v190, v220
	v_readlane_b32 s18, v244, 15
	v_readlane_b32 s19, v244, 16
	v_readlane_b32 s20, v244, 17
	v_readlane_b32 s21, v244, 18
	v_readlane_b32 s23, v244, 20
	s_waitcnt vmcnt(8)
	v_fma_f32 v0, v14, v30, 0
	v_fmac_f32_e32 v0, v15, v31
	s_waitcnt vmcnt(0)
	v_fma_f32 v66, v46, v62, 0
	v_fmac_f32_e32 v66, v47, v63
	v_fmac_f32_e32 v0, v16, v32
	v_fmac_f32_e32 v66, v48, v64
	v_fmac_f32_e32 v0, v17, v33
	v_fmac_f32_e32 v66, v49, v65
	v_fmac_f32_e32 v0, v10, v26
	v_fmac_f32_e32 v66, v42, v58
	v_fmac_f32_e32 v0, v11, v27
	v_fmac_f32_e32 v66, v43, v59
	v_fmac_f32_e32 v0, v12, v28
	v_fmac_f32_e32 v66, v44, v60
	v_fmac_f32_e32 v0, v13, v29
	v_fmac_f32_e32 v66, v45, v61
	v_fmac_f32_e32 v0, v6, v22
	v_fmac_f32_e32 v66, v38, v54
	v_fmac_f32_e32 v0, v7, v23
	v_fmac_f32_e32 v66, v39, v55
	v_fmac_f32_e32 v0, v8, v24
	v_fmac_f32_e32 v66, v40, v56
	v_fmac_f32_e32 v0, v9, v25
	v_fmac_f32_e32 v66, v41, v57
	v_fmac_f32_e32 v0, v2, v18
	v_fmac_f32_e32 v66, v34, v50
	v_fmac_f32_e32 v0, v3, v19
	v_fmac_f32_e32 v66, v35, v51
	v_fmac_f32_e32 v0, v4, v20
	v_fmac_f32_e32 v66, v36, v52
	v_fmac_f32_e32 v0, v5, v21
	v_fmac_f32_e32 v66, v37, v53
	global_load_dwordx4 v[2:5], v1, s[0:1] offset:112
	global_load_dwordx4 v[6:9], v1, s[0:1] offset:96
	global_load_dwordx4 v[10:13], v1, s[0:1] offset:80
	global_load_dwordx4 v[14:17], v1, s[0:1] offset:64
	global_load_dwordx4 v[18:21], v1, s[2:3] offset:112
	global_load_dwordx4 v[22:25], v1, s[2:3] offset:96
	global_load_dwordx4 v[26:29], v1, s[2:3] offset:80
	global_load_dwordx4 v[30:33], v1, s[2:3] offset:64
	global_load_dwordx4 v[34:37], v1, s[4:5] offset:112
	global_load_dwordx4 v[38:41], v1, s[4:5] offset:96
	global_load_dwordx4 v[42:45], v1, s[4:5] offset:80
	global_load_dwordx4 v[46:49], v1, s[4:5] offset:64
	global_load_dwordx4 v[50:53], v1, s[6:7] offset:112
	global_load_dwordx4 v[54:57], v1, s[6:7] offset:96
	global_load_dwordx4 v[58:61], v1, s[6:7] offset:80
	global_load_dwordx4 v[62:65], v1, s[6:7] offset:64
	s_mov_b32 s2, 2.0
	s_mov_b32 s3, 0x40400000
	v_readlane_b32 s4, v245, 35
	v_readlane_b32 s5, v245, 36
	v_readlane_b32 s0, v244, 5
	v_readlane_b32 s1, v244, 6
	s_add_u32 s0, s0, 0x180000
	s_addc_u32 s1, s1, 0
	s_lshl_b32 s14, s16, 5
	s_lshl_b32 s96, s16, 6
	s_add_i32 s22, s84, 63
	s_waitcnt vmcnt(8)
	v_fmac_f32_e32 v0, v14, v30
	s_waitcnt vmcnt(0)
	v_fmac_f32_e32 v66, v46, v62
	v_fmac_f32_e32 v0, v15, v31
	v_fmac_f32_e32 v66, v47, v63
	v_fmac_f32_e32 v0, v16, v32
	v_fmac_f32_e32 v66, v48, v64
	v_fmac_f32_e32 v0, v17, v33
	v_fmac_f32_e32 v66, v49, v65
	v_fmac_f32_e32 v0, v10, v26
	v_fmac_f32_e32 v66, v42, v58
	v_fmac_f32_e32 v0, v11, v27
	v_fmac_f32_e32 v66, v43, v59
	v_fmac_f32_e32 v0, v12, v28
	v_fmac_f32_e32 v66, v44, v60
	v_fmac_f32_e32 v0, v13, v29
	v_fmac_f32_e32 v66, v45, v61
	v_fmac_f32_e32 v0, v6, v22
	v_fmac_f32_e32 v66, v38, v54
	v_fmac_f32_e32 v0, v7, v23
	v_fmac_f32_e32 v66, v39, v55
	v_fmac_f32_e32 v0, v8, v24
	v_fmac_f32_e32 v66, v40, v56
	v_fmac_f32_e32 v0, v9, v25
	v_fmac_f32_e32 v66, v41, v57
	v_fmac_f32_e32 v0, v2, v18
	v_fmac_f32_e32 v66, v34, v50
	v_fmac_f32_e32 v0, v3, v19
	v_fmac_f32_e32 v66, v35, v51
	v_fmac_f32_e32 v0, v4, v20
	v_fmac_f32_e32 v66, v36, v52
	v_fmac_f32_e32 v0, v5, v21
	v_fmac_f32_e32 v66, v37, v53
	v_mul_f32_e32 v0, 0x3fb8aa3b, v0
	v_mul_f32_e32 v2, 0x3fb8aa3b, v66
	v_exp_f32_e32 v0, v0
	v_exp_f32_e32 v2, v2
	v_mov_b32_e32 v13, v1
	v_mov_b32_e32 v21, v1
	v_sub_f32_e32 v0, v0, v2
	v_add_f32_e32 v219, v213, v0
	s_nop 0
	v_readfirstlane_b32 s100, v219
	s_mov_b32 s101, 1
	s_branch .Llam_join
.Llam_cached:
	v_readlane_b32 s0, v245, 61
	v_readlane_b32 s2, v245, 63
	v_readlane_b32 s4, v244, 1
	v_readlane_b32 s6, v244, 3
	v_readlane_b32 s1, v245, 62
	v_readlane_b32 s3, v244, 0
	v_readlane_b32 s5, v244, 2
	v_readlane_b32 s7, v244, 4
	s_nop 1
	s_mov_b32 s10, 0x2aaaaaab
	v_readlane_b32 s16, v244, 13
	v_readlane_b32 s17, v244, 14
	v_readlane_b32 s17, v244, 11
	s_movk_i32 s15, 0x1e00
	s_movk_i32 s11, 0x7f
	v_lshlrev_b32_e32 v159, 6, v151
	v_readlane_b32 s22, v244, 19
	v_lshlrev_b32_e32 v220, 2, v192
	v_lshl_or_b32 v225, v191, 5, 31
	v_sub_u32_e32 v226, v190, v220
	v_readlane_b32 s18, v244, 15
	v_readlane_b32 s19, v244, 16
	v_readlane_b32 s20, v244, 17
	v_readlane_b32 s21, v244, 18
	v_readlane_b32 s23, v244, 20
	s_mov_b32 s2, 2.0
	s_mov_b32 s3, 0x40400000
	v_readlane_b32 s4, v245, 35
	v_readlane_b32 s5, v245, 36
	v_readlane_b32 s0, v244, 5
	v_readlane_b32 s1, v244, 6
	s_add_u32 s0, s0, 0x180000
	s_addc_u32 s1, s1, 0
	s_lshl_b32 s14, s16, 5
	s_lshl_b32 s96, s16, 6
	s_add_i32 s22, s84, 63
	v_mov_b32_e32 v13, v1
	v_mov_b32_e32 v21, v1
	s_waitcnt vmcnt(0)
	v_mov_b32_e32 v219, s100
; DI float ex2(float x) { return __builtin_amdgcn_exp2f(x); }
; DI void fs_init(FS& s) { s.m = -1e30f; s.l = 0.f; s.o0 = zero16(); s.o1 = zero16(); }
; template <int DQK, int NKV, int NCHX>
; DI void stage_load(u32x4 (&reg)[NCHX], const bf16_t* __restrict__ K, int ldk, int kstr, const bf16_t* __restrict__ V, int ldv, int vstr, int kt, int tid) {
;   typedef StageCfg<DQK, NKV> C;
; #pragma unroll
;   for (int i = 0; i < C::NCH; ++i) {
;     const int c = tid + 512 * i, sx = c / C::CS, wi = c % C::CS;
;     const bf16_t* g;
;     if (wi < C::KCH) { const int row = wi / (DQK / 8), ch = wi % (DQK / 8); g = K + (size_t)sx * kstr + (size_t)(kt * 32 + row) * ldk + ch * 8; }
;     else { const int w2 = wi - C::KCH, row = w2 >> 2, ch = w2 & 3; g = V + (size_t)sx * vstr + (size_t)row * ldv + kt * 32 + ch * 8; }
;     reg[i] = *(const u32x4*)g;
;   }
; }
; template <int DQK, int NKV, int NCHX>
; DI void stage_store(const u32x4 (&reg)[NCHX], char* buf, int tid) {
;   typedef StageCfg<DQK, NKV> C;
; #pragma unroll
;   for (int i = 0; i < C::NCH; ++i) {
;     const int c = tid + 512 * i, sx = c / C::CS, wi = c % C::CS;
;     int off;
;     if (wi < C::KCH) { const int row = wi / (DQK / 8), ch = wi % (DQK / 8); off = row * C::KST + ch * 16; }
;     else { const int w2 = wi - C::KCH, row = w2 >> 2, ch = w2 & 3; off = 32 * C::KST + row * 80 + ch * 16; }
;     *(u32x4*)(buf + sx * C::SS + off) = reg[i];
;   }
; DI void attn_unit(const Params& p, int l, int b, int qtp, int grp, char* smem) {
;     ...
;     const float slope2 = ex2(-(2.f / 3.f) * (float)(3 * w + 2)) * LOG2E;
;     const float scale2 = 0.17677669529663687f * LOG2E;
; #pragma unroll 1
;     for (int c = 0; c < 2; ++c) {
;       qf[0] = *(const bf16x8*)(qrow + 1024 + w * 64 + c * 32);
;       qf[1] = *(const bf16x8*)(qrow + 1024 + w * 64 + c * 32 + 16);
;       FS st; fs_init(st);
;       flash_block<32, 4>(st, qf, w, Kb + 1280 + c * 32, QKW, 64, VT + (size_t)384 * SEQ, SEQ, 64 * SEQ, 0, qtb, 0, qt, q0, qpos, INFW, scale2, slope2, 0u, false, tbuf, bum, tid, r, h);
.Llam_join:
	v_mad_u32_u24 v0, v151, 3, 2
	v_cvt_f32_ubyte0_e32 v0, v0
	v_mul_f32_e32 v0, 0xbf2aaaab, v0
	v_exp_f32_e32 v0, v0
	s_nop 0
	v_mul_f32_e32 v123, 0x3fb8aa3b, v0
	v_lshlrev_b32_e32 v0, 7, v151
	v_lshl_add_u64 v[124:125], v[162:163], 0, v[0:1]
	v_mov_b32_e32 v0, v123
	v_pk_mul_f32 v[126:127], v[0:1], s[2:3] op_sel_hi:[0,1]
	s_mov_b32 s2, 0x41000000
	s_mov_b32 s3, 0x41100000
	v_pk_mul_f32 v[128:129], v[0:1], s[2:3] op_sel_hi:[0,1]
	s_mov_b32 s2, 0x41200000
	s_mov_b32 s3, 0x41300000
	v_pk_mul_f32 v[130:131], v[0:1], s[2:3] op_sel_hi:[0,1]
	v_readlane_b32 s2, v245, 33
	v_readlane_b32 s3, v245, 34
	s_mov_b32 s2, s5
	s_mov_b32 s5, s3
	v_pk_mul_f32 v[132:133], v[0:1], s[2:3] op_sel_hi:[0,1]
	s_mov_b32 s2, 0x41900000
	s_mov_b32 s3, 0x41980000
	v_pk_mul_f32 v[134:135], v[0:1], s[2:3] op_sel_hi:[0,1]
	s_mov_b32 s2, 0x41c00000
	s_mov_b32 s3, 0x41c80000
	v_pk_mul_f32 v[136:137], v[0:1], s[2:3] op_sel_hi:[0,1]
	s_mov_b32 s2, 0x41d00000
	s_mov_b32 s3, 0x41d80000
	v_pk_mul_f32 v[138:139], v[0:1], s[2:3] op_sel_hi:[0,1]
	v_mul_hi_i32 v0, v193, s10
	v_lshrrev_b32_e32 v2, 31, v0
	v_ashrrev_i32_e32 v0, 6, v0
	v_add_u32_e32 v2, v0, v2
	v_mul_i32_i24_e32 v0, 0x180, v2
	v_sub_u32_e32 v5, v193, v0
	v_add_u32_e32 v0, 0x200, v193
	v_mul_hi_i32 v3, v0, s10
	v_lshrrev_b32_e32 v4, 31, v3
	v_ashrrev_i32_e32 v3, 6, v3
	v_add_u32_e32 v4, v3, v4
	v_mul_i32_i24_e32 v3, 0x180, v4
	v_sub_u32_e32 v7, v0, v3
	v_add_u32_e32 v0, 0x400, v193
	v_mul_hi_i32 v3, v0, s10
	v_lshrrev_b32_e32 v6, 31, v3
	v_ashrrev_i32_e32 v3, 6, v3
	v_add_u32_e32 v6, v3, v6
	v_mul_i32_i24_e32 v3, 0x180, v6
	v_sub_u32_e32 v24, v0, v3
	v_mov_b32_e32 v0, s17
	v_ashrrev_i16_e32 v12, 15, v5
	v_mad_i32_i24 v25, v2, s15, v0
	v_mad_i32_i24 v26, v4, s15, v0
	v_mad_i32_i24 v27, v6, s15, v0
	v_add_u32_e32 v0, 0xffffff80, v5
	v_ashrrev_i32_e32 v3, 31, v2
	v_lshrrev_b16_e32 v12, 14, v12
	v_lshrrev_b32_e32 v0, 2, v0
	v_lshlrev_b64 v[8:9], 18, v[2:3]
	v_add_u16_e32 v12, v5, v12
	v_writelane_b32 v245, s4, 33
	v_lshl_add_u64 v[8:9], s[0:1], 0, v[8:9]
	v_lshlrev_b64 v[10:11], 12, v[0:1]
	v_ashrrev_i16_e32 v221, 2, v12
	v_and_b32_e32 v12, -4, v12
	v_writelane_b32 v245, s5, 34
	v_cmp_lt_i32_e64 s[2:3], s11, v5
	v_cmp_gt_i32_e64 s[4:5], s72, v5
	v_lshl_add_u64 v[8:9], v[8:9], 0, v[10:11]
	v_lshlrev_b32_e32 v10, 4, v5
	v_sub_u16_e32 v5, v5, v12
	v_bfe_i32 v28, v5, 0, 16
	v_add_u32_e32 v5, 0xffffff80, v7
	v_lshrrev_b32_e32 v12, 2, v5
	v_ashrrev_i32_e32 v5, 31, v4
	v_lshlrev_b64 v[14:15], 18, v[4:5]
	v_lshl_add_u64 v[14:15], s[0:1], 0, v[14:15]
	v_lshlrev_b64 v[16:17], 12, v[12:13]
	v_lshlrev_b32_e32 v13, 4, v7
	v_lshl_add_u64 v[14:15], v[14:15], 0, v[16:17]
	v_and_b32_e32 v16, 48, v13
	v_ashrrev_i16_e32 v13, 15, v7
	v_lshrrev_b16_e32 v13, 14, v13
	v_add_u16_e32 v13, v7, v13
	v_ashrrev_i16_e32 v222, 2, v13
	v_and_b32_e32 v13, -4, v13
	v_cmp_lt_i32_e64 s[6:7], s11, v7
	v_cmp_gt_i32_e64 s[8:9], s72, v7
	v_sub_u16_e32 v7, v7, v13
	v_bfe_i32 v13, v7, 0, 16
	v_ashrrev_i32_e32 v7, 31, v6
	v_lshlrev_b64 v[18:19], 18, v[6:7]
	v_lshlrev_b64 v[148:149], 7, v[6:7]
	v_mul_u32_u24_e32 v6, 0x1e00, v151
	v_mul_u32_u24_e32 v7, 0x50, v190
	v_add3_u32 v223, s17, v6, v7
	v_mul_lo_u16_e32 v6, 0x50, v221
	v_and_b32_e32 v10, 48, v10
	v_lshl_add_u64 v[18:19], s[0:1], 0, v[18:19]
	v_mul_lo_u32 v0, v0, s80
	s_movk_i32 s0, 0xa00
	v_bfe_i32 v6, v6, 0, 16
	v_add3_u32 v0, v0, v10, s0
	v_lshl_add_u32 v6, v28, 4, v6
	v_mul_lo_u32 v7, v12, s80
	v_mul_lo_u16_e32 v12, 0x50, v222
	v_lshlrev_b64 v[142:143], 7, v[2:3]
	v_lshlrev_b32_e32 v2, 3, v28
	v_bfe_i32 v12, v12, 0, 16
	v_cndmask_b32_e64 v28, v0, v6, s[4:5]
	v_add_u32_sdwa v0, s14, sext(v221) dst_sel:DWORD dst_unused:UNUSED_PAD src0_sel:DWORD src1_sel:WORD_0
	v_add3_u32 v7, v7, v16, s0
	v_lshl_add_u32 v12, v13, 4, v12
	v_mul_i32_i24_e32 v162, 0xf00, v0
	v_add_u32_sdwa v0, s14, sext(v222) dst_sel:DWORD dst_unused:UNUSED_PAD src0_sel:DWORD src1_sel:WORD_0
	v_mov_b32_e32 v11, v1
	v_cndmask_b32_e64 v30, v7, v12, s[8:9]
	v_lshl_add_u64 v[6:7], v[8:9], 0, s[96:97]
	v_mul_i32_i24_e32 v166, 0xf00, v0
	v_add_u32_e32 v0, 0xffffff80, v24
	v_mov_b32_e32 v17, v1
	v_lshlrev_b32_e32 v20, 3, v24
	v_lshl_add_u64 v[150:151], v[6:7], 0, v[10:11]
	v_lshl_add_u64 v[6:7], v[14:15], 0, s[96:97]
	v_lshrrev_b32_e32 v0, 2, v0
	v_and_b32_e32 v29, 24, v20
	v_lshl_add_u64 v[164:165], v[6:7], 0, v[16:17]
	v_lshlrev_b64 v[6:7], 12, v[0:1]
	v_lshlrev_b64 v[146:147], 7, v[4:5]
	v_lshlrev_b32_e32 v4, 3, v13
	v_lshlrev_b32_e32 v20, 1, v29
	v_lshl_add_u64 v[12:13], v[18:19], 0, v[6:7]
	v_lshl_add_u64 v[22:23], v[18:19], 0, v[20:21]
	v_lshl_add_u64 v[18:19], v[12:13], 0, s[96:97]
	s_lshl_b32 s96, s84, 1
	v_lshl_add_u64 v[140:141], v[8:9], 0, v[10:11]
	v_lshl_add_u64 v[8:9], v[8:9], 0, s[96:97]
	v_lshl_add_u64 v[168:169], v[18:19], 0, v[20:21]
	v_ashrrev_i16_e32 v18, 15, v24
	v_lshl_add_u64 v[172:173], v[8:9], 0, v[10:11]
	v_add_u32_sdwa v8, s84, sext(v221) dst_sel:DWORD dst_unused:UNUSED_PAD src0_sel:DWORD src1_sel:WORD_0
	v_lshrrev_b16_e32 v18, 14, v18
	v_mul_i32_i24_e32 v174, 0xf00, v8
	v_lshl_add_u64 v[8:9], v[14:15], 0, s[96:97]
	v_add_u16_e32 v18, v24, v18
	v_lshl_add_u64 v[176:177], v[8:9], 0, v[16:17]
	v_add_u32_sdwa v8, s84, sext(v222) dst_sel:DWORD dst_unused:UNUSED_PAD src0_sel:DWORD src1_sel:WORD_0
	v_ashrrev_i16_e32 v224, 2, v18
	v_mul_i32_i24_e32 v178, 0xf00, v8
	v_lshl_add_u64 v[8:9], v[12:13], 0, s[96:97]
	v_lshl_add_u64 v[180:181], v[8:9], 0, v[20:21]
	v_add_u32_sdwa v8, s84, sext(v224) dst_sel:DWORD dst_unused:UNUSED_PAD src0_sel:DWORD src1_sel:WORD_0
	v_mul_i32_i24_e32 v182, 0xf00, v8
	v_lshlrev_b32_e32 v8, 4, v24
	v_and_b32_e32 v18, -4, v18
	v_mul_lo_u32 v0, v0, s80
	v_and_b32_e32 v8, 48, v8
	v_sub_u16_e32 v18, v24, v18
	v_add3_u32 v0, v0, v8, s0
	v_mul_lo_u16_e32 v8, 0x50, v224
	v_bfe_i32 v31, v18, 0, 16
	v_add_u32_sdwa v18, s14, sext(v224) dst_sel:DWORD dst_unused:UNUSED_PAD src0_sel:DWORD src1_sel:WORD_0
	v_bfe_i32 v8, v8, 0, 16
	v_cmp_gt_i32_e64 s[12:13], s72, v24
	v_mul_i32_i24_e32 v170, 0xf00, v18
	v_lshlrev_b32_e32 v18, 3, v31
	v_lshl_add_u32 v8, v31, 4, v8
	v_ashrrev_i32_e32 v3, 31, v2
	v_ashrrev_i32_e32 v5, 31, v4
	v_ashrrev_i32_e32 v19, 31, v18
	v_cndmask_b32_e64 v0, v0, v8, s[12:13]
	v_mul_f32_e32 v122, 0, v123
	v_cmp_lt_i32_e64 s[10:11], s11, v24
	v_lshl_add_u64 v[144:145], v[14:15], 0, v[16:17]
	v_ashrrev_i32_e32 v163, 31, v162
	v_ashrrev_i32_e32 v167, 31, v166
	v_ashrrev_i32_e32 v171, 31, v170
	v_ashrrev_i32_e32 v175, 31, v174
	v_ashrrev_i32_e32 v179, 31, v178
	v_ashrrev_i32_e32 v183, 31, v182
	v_lshl_add_u64 v[184:185], v[22:23], 0, v[6:7]
	v_cndmask_b32_e64 v187, 0, v19, s[12:13]
	v_cndmask_b32_e64 v186, v29, v18, s[12:13]
	s_mov_b64 s[14:15], 0
	s_mov_b64 s[0:1], -1
	v_lshlrev_b64 v[188:189], 1, v[2:3]
	v_lshlrev_b64 v[190:191], 1, v[4:5]
	v_lshlrev_b64 v[192:193], 1, v[18:19]
	v_add_u32_e32 v227, v25, v28
	v_add_u32_e32 v228, v26, v30
	v_add_u32_e32 v229, v27, v0
	s_branch .LBB0_439

; #define MFMA(a, b, c) __builtin_amdgcn_mfma_f32_32x32x16_bf16((a), (b), (c), 0, 0, 0)
; DI unsigned pk2(float a, float b) { f32x2 v = {a, b}; bf2_t r = __builtin_convertvector(v, bf2_t); return __builtin_bit_cast(unsigned, r); }
; DI bf16_t f2bf(float a) { return (bf16_t)(pk2(a, 0.f) & 0xffffu); }
; DI f32x16 zero16() { f32x16 z; _Pragma("unroll") for (int i = 0; i < 16; ++i) z[i] = 0.f; return z; }
; DI void phase_cmp(const Params& p, int l, char* smem) {
;     ...
;     if (kh == 0 && w < 2) {
;       const bf16_t* w2 = (const bf16_t*)(p.ws + OFF_W2T) + ((size_t)lk * 64 + 32 * w + r) * 128 + 8 * h;
;       f32x16 a2 = zero16();
; #pragma unroll
;       for (int ks = 0; ks < 8; ++ks) {
;         const bf16x8 a = *(const bf16x8*)(hid + r * 136 + ks * 16 + 8 * h);
;         const bf16x8 bb = *(const bf16x8*)(w2 + ks * 16);
;         a2 = MFMA(a, bb, a2);
;       }
;       if (kv == 0) {
;         bf16_t* kc = (bf16_t*)(p.ws + OFF_KCMP) + (size_t)b * 128 * 64;
; #pragma unroll
;         for (int i = 0; i < 16; ++i) { const int m = (i & 3) + 8 * (i >> 2) + 4 * h; kc[(rt * 32 + m) * 64 + 32 * w + r] = f2bf(a2[i]); }
;       } else {
;         bf16_t* vc = (bf16_t*)(p.ws + OFF_VCMP) + (size_t)b * 64 * 128;
; #pragma unroll
;         for (int g = 0; g < 4; ++g) {
;           u32x2 o = {pk2(a2[4 * g], a2[4 * g + 1]), pk2(a2[4 * g + 2], a2[4 * g + 3])};
;           *(u32x2*)(vc + (32 * w + r) * 128 + rt * 32 + 8 * g + 4 * h) = o;
;         }
.LBB0_510:
	s_or_b64 exec, exec, s[12:13]
	s_waitcnt lgkmcnt(0)
	s_barrier
	s_and_saveexec_b64 s[12:13], s[0:1]
	s_cbranch_execz .LBB0_501
	s_or_b32 s14, s14, s16
	s_ashr_i32 s15, s14, 31
	s_lshl_b64 s[14:15], s[14:15], 14
	v_lshl_or_b32 v2, v20, 8, s14
	v_mov_b32_e32 v3, s15
	v_lshl_add_u64 v[42:43], v[22:23], 0, v[2:3]
	global_load_dwordx4 v[60:63], v[42:43], off
	global_load_dwordx4 v[64:67], v[42:43], off offset:32
	global_load_dwordx4 v[68:71], v[42:43], off offset:64
	global_load_dwordx4 v[72:75], v[42:43], off offset:96
	global_load_dwordx4 v[76:79], v[42:43], off offset:128
	global_load_dwordx4 v[80:83], v[42:43], off offset:160
	global_load_dwordx4 v[84:87], v[42:43], off offset:192
	global_load_dwordx4 v[88:91], v[42:43], off offset:224
	ds_read_b128 v[92:95], v34
	ds_read_b128 v[96:99], v34 offset:32
	ds_read_b128 v[100:103], v34 offset:64
	ds_read_b128 v[104:107], v34 offset:96
	ds_read_b128 v[108:111], v34 offset:128
	ds_read_b128 v[112:115], v34 offset:160
	ds_read_b128 v[116:119], v34 offset:192
	ds_read_b128 v[120:123], v34 offset:224
	s_lshl_b64 s[8:9], s[8:9], 14
	s_mov_b64 s[14:15], -1
	s_and_b64 vcc, exec, s[10:11]
	s_waitcnt vmcnt(7) lgkmcnt(7)
	v_mfma_f32_32x32x16_bf16 v[2:17], v[92:95], v[60:63], 0
	s_waitcnt vmcnt(6) lgkmcnt(6)
	v_mfma_f32_32x32x16_bf16 v[2:17], v[96:99], v[64:67], v[2:17]
	s_waitcnt vmcnt(5) lgkmcnt(5)
	v_mfma_f32_32x32x16_bf16 v[2:17], v[100:103], v[68:71], v[2:17]
	s_waitcnt vmcnt(4) lgkmcnt(4)
	v_mfma_f32_32x32x16_bf16 v[2:17], v[104:107], v[72:75], v[2:17]
	s_waitcnt vmcnt(3) lgkmcnt(3)
	v_mfma_f32_32x32x16_bf16 v[2:17], v[108:111], v[76:79], v[2:17]
	s_waitcnt vmcnt(2) lgkmcnt(2)
	v_mfma_f32_32x32x16_bf16 v[2:17], v[112:115], v[80:83], v[2:17]
	s_waitcnt vmcnt(1) lgkmcnt(1)
	v_mfma_f32_32x32x16_bf16 v[2:17], v[116:119], v[84:87], v[2:17]
	s_waitcnt vmcnt(0) lgkmcnt(0)
	v_mfma_f32_32x32x16_bf16 v[2:17], v[120:123], v[88:91], v[2:17]
	s_cbranch_vccz .LBB0_513
	v_lshl_add_u64 v[28:29], v[24:25], 0, s[8:9]
	s_lshl_b32 s96, s18, 1
	v_lshl_add_u64 v[28:29], v[28:29], 0, s[96:97]
	v_lshlrev_b32_e32 v30, 1, v18
	v_mov_b32_e32 v31, v1
	v_lshl_add_u64 v[28:29], v[28:29], 0, v[30:31]
	s_nop 4
	v_cvt_pk_bf16_f32 v30, v2, v3
	v_cvt_pk_bf16_f32 v31, v4, v5
	global_store_dwordx2 v[28:29], v[30:31], off
	v_cvt_pk_bf16_f32 v30, v6, v7
	v_cvt_pk_bf16_f32 v31, v8, v9
	global_store_dwordx2 v[28:29], v[30:31], off offset:16
	v_cvt_pk_bf16_f32 v30, v10, v11
	v_cvt_pk_bf16_f32 v31, v12, v13
	global_store_dwordx2 v[28:29], v[30:31], off offset:32
	v_cvt_pk_bf16_f32 v30, v14, v15
	v_cvt_pk_bf16_f32 v31, v16, v17
	global_store_dwordx2 v[28:29], v[30:31], off offset:48
	s_mov_b64 s[14:15], 0

; __global__ void __launch_bounds__(512, 2) mega(Params p) {
;   __shared__ __attribute__((aligned(16))) char smem[163328];
	.amdhsa_kernel _Z4mega6Params
		.amdhsa_group_segment_fixed_size 163584
		.amdhsa_private_segment_fixed_size 0
		.amdhsa_kernarg_size 440
		.amdhsa_user_sgpr_count 2
		.amdhsa_user_sgpr_dispatch_ptr 0
		.amdhsa_user_sgpr_queue_ptr 0
		.amdhsa_user_sgpr_kernarg_segment_ptr 1
		.amdhsa_user_sgpr_dispatch_id 0
		.amdhsa_user_sgpr_kernarg_preload_length 0
		.amdhsa_user_sgpr_kernarg_preload_offset 0
		.amdhsa_user_sgpr_private_segment_size 0
		.amdhsa_uses_dynamic_stack 0
		.amdhsa_enable_private_segment 0
		.amdhsa_system_sgpr_workgroup_id_x 1
		.amdhsa_system_sgpr_workgroup_id_y 0
		.amdhsa_system_sgpr_workgroup_id_z 0
		.amdhsa_system_sgpr_workgroup_info 0
		.amdhsa_system_vgpr_workitem_id 2
		.amdhsa_next_free_vgpr 256
		.amdhsa_next_free_sgpr 102
		.amdhsa_accum_offset 256
		.amdhsa_reserve_vcc 1
		.amdhsa_float_round_mode_32 0
		.amdhsa_float_round_mode_16_64 0
		.amdhsa_float_denorm_mode_32 3
		.amdhsa_float_denorm_mode_16_64 3
		.amdhsa_dx10_clamp 1
		.amdhsa_ieee_mode 1
		.amdhsa_fp16_overflow 0
		.amdhsa_tg_split 0
		.amdhsa_exception_fp_ieee_invalid_op 0
		.amdhsa_exception_fp_denorm_src 0
		.amdhsa_exception_fp_ieee_div_zero 0
		.amdhsa_exception_fp_ieee_overflow 0
		.amdhsa_exception_fp_ieee_underflow 0
		.amdhsa_exception_fp_ieee_inexact 0
		.amdhsa_exception_int_div_zero 0
	.end_amdhsa_kernel

; __global__ void __launch_bounds__(512, 2) mega(Params p) {
;   __shared__ __attribute__((aligned(16))) char smem[163328];
amdhsa.kernels:
  - .agpr_count:     0
    .args:
      - .offset:         0
        .size:           184
        .value_kind:     by_value
      - .offset:         184
        .size:           4
        .value_kind:     hidden_block_count_x
      - .offset:         188
        .size:           4
        .value_kind:     hidden_block_count_y
      - .offset:         192
        .size:           4
        .value_kind:     hidden_block_count_z
      - .offset:         196
        .size:           2
        .value_kind:     hidden_group_size_x
      - .offset:         198
        .size:           2
        .value_kind:     hidden_group_size_y
      - .offset:         200
        .size:           2
        .value_kind:     hidden_group_size_z
      - .offset:         202
        .size:           2
        .value_kind:     hidden_remainder_x
      - .offset:         204
        .size:           2
        .value_kind:     hidden_remainder_y
      - .offset:         206
        .size:           2
        .value_kind:     hidden_remainder_z
      - .offset:         224
        .size:           8
        .value_kind:     hidden_global_offset_x
      - .offset:         232
        .size:           8
        .value_kind:     hidden_global_offset_y
      - .offset:         240
        .size:           8
        .value_kind:     hidden_global_offset_z
      - .offset:         248
        .size:           2
        .value_kind:     hidden_grid_dims
      - .offset:         272
        .size:           8
        .value_kind:     hidden_multigrid_sync_arg
    .group_segment_fixed_size: 163584
    .kernarg_segment_align: 8
    .kernarg_segment_size: 440
    .language:       OpenCL C
    .language_version:
      - 2
      - 0
    .max_flat_workgroup_size: 512
    .name:           _Z4mega6Params
    .private_segment_fixed_size: 0
    .sgpr_count:     108
    .sgpr_spill_count: 248
    .symbol:         _Z4mega6Params.kd
    .uniform_work_group_size: 1
    .uses_dynamic_stack: false
    .vgpr_count:     256
    .vgpr_spill_count: 0
    .wavefront_size: 64
